# phase_prep: p -> bf16 conversion with 16 loads in flight per thread before the one-load-per-round-trip loop (kept as tail)
# speedup vs baseline: 1.0121x; 1.0033x over previous
.LBB0_90:
	s_mov_b32 s97, 0
	s_waitcnt vmcnt(4)
	v_mbcnt_lo_u32_b32 v2, -1, v40
	v_mbcnt_hi_u32_b32 v2, -1, v2
	v_add_u32_e32 v2, s85, v2
	s_lshl_b64 s[2:3], s[96:97], 9
	v_ashrrev_i32_e32 v3, 31, v2
	v_lshl_add_u64 v[2:3], s[2:3], 0, v[2:3]
	s_mov_b64 s[2:3], 0x400000
	v_cmp_gt_u64_e32 vcc, s[2:3], v[2:3]
	s_and_saveexec_b64 s[10:11], vcc
	s_cbranch_execz .LBB0_93
	s_load_dwordx2 s[2:3], s[4:5], 0x8
	s_mov_b32 s16, s94
	s_mov_b32 s17, s97
	s_waitcnt lgkmcnt(0)
	v_lshl_add_u64 v[4:5], v[2:3], 3, s[6:7]
	s_mov_b64 s[14:15], 0xb800000
	s_lshl_b64 s[12:13], s[16:17], 9
	v_lshl_add_u64 v[4:5], v[4:5], 0, s[14:15]
	s_lshl_b64 s[14:15], s[16:17], 12
	v_lshl_add_u64 v[6:7], v[2:3], 4, s[2:3]
	s_lshl_b64 s[16:17], s[16:17], 13
	s_mov_b64 s[18:19], 0
	s_mov_b64 s[20:21], 0x3fffff
	s_lshl_b64 s[22:23], s[12:13], 4
	s_sub_u32 s24, s22, s12
	s_subb_u32 s25, s23, s13
	s_lshl_b64 s[26:27], s[14:15], 4
	s_lshl_b64 s[28:29], s[16:17], 4
.Lpb_batch:
	v_lshl_add_u64 v[248:249], v[2:3], 0, s[24:25]
	v_cmp_ge_u64_e32 vcc, s[20:21], v[248:249]
	s_xor_b64 s[30:31], vcc, exec
	s_cmp_lg_u64 s[30:31], 0
	s_cbranch_scc1 .Lpb_tail
	global_load_dwordx4 v[180:183], v[6:7], off
	v_lshl_add_u64 v[244:245], v[6:7], 0, s[16:17]
	global_load_dwordx4 v[184:187], v[244:245], off
	v_lshl_add_u64 v[244:245], v[244:245], 0, s[16:17]
	global_load_dwordx4 v[188:191], v[244:245], off
	v_lshl_add_u64 v[244:245], v[244:245], 0, s[16:17]
	global_load_dwordx4 v[192:195], v[244:245], off
	v_lshl_add_u64 v[244:245], v[244:245], 0, s[16:17]
	global_load_dwordx4 v[196:199], v[244:245], off
	v_lshl_add_u64 v[244:245], v[244:245], 0, s[16:17]
	global_load_dwordx4 v[200:203], v[244:245], off
	v_lshl_add_u64 v[244:245], v[244:245], 0, s[16:17]
	global_load_dwordx4 v[204:207], v[244:245], off
	v_lshl_add_u64 v[244:245], v[244:245], 0, s[16:17]
	global_load_dwordx4 v[208:211], v[244:245], off
	v_lshl_add_u64 v[244:245], v[244:245], 0, s[16:17]
	global_load_dwordx4 v[212:215], v[244:245], off
	v_lshl_add_u64 v[244:245], v[244:245], 0, s[16:17]
	global_load_dwordx4 v[216:219], v[244:245], off
	v_lshl_add_u64 v[244:245], v[244:245], 0, s[16:17]
	global_load_dwordx4 v[220:223], v[244:245], off
	v_lshl_add_u64 v[244:245], v[244:245], 0, s[16:17]
	global_load_dwordx4 v[224:227], v[244:245], off
	v_lshl_add_u64 v[244:245], v[244:245], 0, s[16:17]
	global_load_dwordx4 v[228:231], v[244:245], off
	v_lshl_add_u64 v[244:245], v[244:245], 0, s[16:17]
	global_load_dwordx4 v[232:235], v[244:245], off
	v_lshl_add_u64 v[244:245], v[244:245], 0, s[16:17]
	global_load_dwordx4 v[236:239], v[244:245], off
	v_lshl_add_u64 v[244:245], v[244:245], 0, s[16:17]
	global_load_dwordx4 v[240:243], v[244:245], off
	s_waitcnt vmcnt(0)
	v_cvt_pk_bf16_f32 v180, v180, v181
	v_cvt_pk_bf16_f32 v181, v182, v183
	global_store_dwordx2 v[4:5], v[180:181], off
	v_lshl_add_u64 v[246:247], v[4:5], 0, s[14:15]
	v_cvt_pk_bf16_f32 v184, v184, v185
	v_cvt_pk_bf16_f32 v185, v186, v187
	global_store_dwordx2 v[246:247], v[184:185], off
	v_lshl_add_u64 v[246:247], v[246:247], 0, s[14:15]
	v_cvt_pk_bf16_f32 v188, v188, v189
	v_cvt_pk_bf16_f32 v189, v190, v191
	global_store_dwordx2 v[246:247], v[188:189], off
	v_lshl_add_u64 v[246:247], v[246:247], 0, s[14:15]
	v_cvt_pk_bf16_f32 v192, v192, v193
	v_cvt_pk_bf16_f32 v193, v194, v195
	global_store_dwordx2 v[246:247], v[192:193], off
	v_lshl_add_u64 v[246:247], v[246:247], 0, s[14:15]
	v_cvt_pk_bf16_f32 v196, v196, v197
	v_cvt_pk_bf16_f32 v197, v198, v199
	global_store_dwordx2 v[246:247], v[196:197], off
	v_lshl_add_u64 v[246:247], v[246:247], 0, s[14:15]
	v_cvt_pk_bf16_f32 v200, v200, v201
	v_cvt_pk_bf16_f32 v201, v202, v203
	global_store_dwordx2 v[246:247], v[200:201], off
	v_lshl_add_u64 v[246:247], v[246:247], 0, s[14:15]
	v_cvt_pk_bf16_f32 v204, v204, v205
	v_cvt_pk_bf16_f32 v205, v206, v207
	global_store_dwordx2 v[246:247], v[204:205], off
	v_lshl_add_u64 v[246:247], v[246:247], 0, s[14:15]
	v_cvt_pk_bf16_f32 v208, v208, v209
	v_cvt_pk_bf16_f32 v209, v210, v211
	global_store_dwordx2 v[246:247], v[208:209], off
	v_lshl_add_u64 v[246:247], v[246:247], 0, s[14:15]
	v_cvt_pk_bf16_f32 v212, v212, v213
	v_cvt_pk_bf16_f32 v213, v214, v215
	global_store_dwordx2 v[246:247], v[212:213], off
	v_lshl_add_u64 v[246:247], v[246:247], 0, s[14:15]
	v_cvt_pk_bf16_f32 v216, v216, v217
	v_cvt_pk_bf16_f32 v217, v218, v219
	global_store_dwordx2 v[246:247], v[216:217], off
	v_lshl_add_u64 v[246:247], v[246:247], 0, s[14:15]
	v_cvt_pk_bf16_f32 v220, v220, v221
	v_cvt_pk_bf16_f32 v221, v222, v223
	global_store_dwordx2 v[246:247], v[220:221], off
	v_lshl_add_u64 v[246:247], v[246:247], 0, s[14:15]
	v_cvt_pk_bf16_f32 v224, v224, v225
	v_cvt_pk_bf16_f32 v225, v226, v227
	global_store_dwordx2 v[246:247], v[224:225], off
	v_lshl_add_u64 v[246:247], v[246:247], 0, s[14:15]
	v_cvt_pk_bf16_f32 v228, v228, v229
	v_cvt_pk_bf16_f32 v229, v230, v231
	global_store_dwordx2 v[246:247], v[228:229], off
	v_lshl_add_u64 v[246:247], v[246:247], 0, s[14:15]
	v_cvt_pk_bf16_f32 v232, v232, v233
	v_cvt_pk_bf16_f32 v233, v234, v235
	global_store_dwordx2 v[246:247], v[232:233], off
	v_lshl_add_u64 v[246:247], v[246:247], 0, s[14:15]
	v_cvt_pk_bf16_f32 v236, v236, v237
	v_cvt_pk_bf16_f32 v237, v238, v239
	global_store_dwordx2 v[246:247], v[236:237], off
	v_lshl_add_u64 v[246:247], v[246:247], 0, s[14:15]
	v_cvt_pk_bf16_f32 v240, v240, v241
	v_cvt_pk_bf16_f32 v241, v242, v243
	global_store_dwordx2 v[246:247], v[240:241], off
	v_lshl_add_u64 v[2:3], v[2:3], 0, s[22:23]
	v_lshl_add_u64 v[6:7], v[6:7], 0, s[28:29]
	v_lshl_add_u64 v[4:5], v[4:5], 0, s[26:27]
	s_branch .Lpb_batch
.Lpb_tail:
	v_cmp_ge_u64_e32 vcc, s[20:21], v[2:3]
	s_and_b64 exec, exec, vcc
	s_cbranch_execz .LBB0_93
